# prompt attention: skip the always-true window-mask sequences of key blocks 1 and 2 when the unit is not first in its sequence
# speedup vs baseline: 1.0018x; 1.0018x over previous
; __device__ __forceinline__ float xor32_max(float v) { float a = v, b = v; asm volatile("s_nop 1\n\tv_permlane32_swap_b32 %0, %1\n\ts_nop 1" : "+v"(a), "+v"(b)); return fmaxf(a, b); }
; __device__ __forceinline__ void attn_prompt_unit(unsigned char* lds, const bf16_t* Q, const bf16_t* Kb, const bf16_t* Vb, bf16_t* MIX, const float* sinks, int unit, int tid) {
;     ...
;         const int q0 = 64 * hh + 32 * qs, qi = q0 + l32;
;         const size_t qrow = (size_t)b * SEQ + nb * 128 + qi;
;         bf16x8 qf[4];
; #pragma unroll
;         for (int ks = 0; ks < 4; ++ks) qf[ks] = *(const bf16x8*)(Q + qrow * 512 + head * 64 + ks * 16 + hi * 8);
;         f32x16 S[5];
; #pragma unroll
;         for (int kb = 0; kb < 5; ++kb) { f32x16 a = {0.f,0.f,0.f,0.f,0.f,0.f,0.f,0.f,0.f,0.f,0.f,0.f,0.f,0.f,0.f,0.f};
;             const unsigned char* kp = lds + ATT_KS + (q0 + 32 * kb + l32) * KS_PITCH + hi * 16;
; #pragma unroll
;             for (int ks = 0; ks < 4; ++ks) { const bf16x8 kf = *(const bf16x8*)(kp + ks * 32); a = __builtin_amdgcn_mfma_f32_32x32x16_bf16(kf, qf[ks], a, 0, 0, 0); }
;             S[kb] = a; }
;         float mx = -1e30f;
; #pragma unroll
;         for (int kb = 0; kb < 5; ++kb)
; #pragma unroll
;             for (int r = 0; r < 16; ++r) { const int kj = q0 + 32 * kb + (r & 3) + 8 * (r >> 2) + 4 * hi; const int rel = 128 + qi - kj;
;                 const bool ok = (rel >= 0) && (rel < 128) && (nb > 0 || kj >= 128);
;                 const float s = ok ? S[kb][r] : -1e30f; S[kb][r] = s; mx = fmaxf(mx, s); }
;         mx = fmaxf(xor32_max(mx), sink);
.LBB0_937:
	v_or_b32_e32 v130, s16, v145
	v_or_b32_e32 v12, v130, v141
	v_ashrrev_i32_e32 v13, 31, v12
	v_lshl_add_u64 v[94:95], s[6:7], 0, v[12:13]
	v_lshlrev_b64 v[0:1], 10, v[94:95]
	v_lshl_add_u64 v[4:5], v[90:91], 0, v[0:1]
	global_load_dwordx4 v[0:3], v[4:5], off
	global_load_dwordx4 v[132:135], v[4:5], off offset:32
	global_load_dwordx4 v[136:139], v[4:5], off offset:64
	global_load_dwordx4 v[148:151], v[4:5], off offset:96
	v_mad_u64_u32 v[128:129], s[0:1], v12, s86, v[86:87]
	ds_read_b128 v[4:7], v128
	ds_read_b128 v[8:11], v128 offset:32
	v_add_u32_e32 v129, 0x80, v12
	s_waitcnt vmcnt(3) lgkmcnt(1)
	v_mfma_f32_32x32x16_bf16 v[64:79], v[4:7], v[0:3], 0
	ds_read_b128 v[4:7], v128 offset:64
	ds_read_b128 v[152:155], v128 offset:18464
	s_waitcnt vmcnt(2) lgkmcnt(2)
	v_mfma_f32_32x32x16_bf16 v[64:79], v[8:11], v[132:135], v[64:79]
	s_waitcnt vmcnt(1) lgkmcnt(1)
	v_mfma_f32_32x32x16_bf16 v[64:79], v[4:7], v[136:139], v[64:79]
	ds_read_b128 v[4:7], v128 offset:96
	s_waitcnt vmcnt(0) lgkmcnt(0)
	v_mfma_f32_32x32x16_bf16 v[64:79], v[4:7], v[148:151], v[64:79]
	ds_read_b128 v[4:7], v128 offset:4608
	s_waitcnt lgkmcnt(0)
	v_mfma_f32_32x32x16_bf16 v[48:63], v[4:7], v[0:3], 0
	ds_read_b128 v[4:7], v128 offset:4640
	s_waitcnt lgkmcnt(0)
	v_mfma_f32_32x32x16_bf16 v[48:63], v[4:7], v[132:135], v[48:63]
	ds_read_b128 v[4:7], v128 offset:4672
	s_waitcnt lgkmcnt(0)
	v_mfma_f32_32x32x16_bf16 v[48:63], v[4:7], v[136:139], v[48:63]
	ds_read_b128 v[4:7], v128 offset:4704
	s_waitcnt lgkmcnt(0)
	v_mfma_f32_32x32x16_bf16 v[48:63], v[4:7], v[148:151], v[48:63]
	ds_read_b128 v[4:7], v128 offset:9216
	s_waitcnt lgkmcnt(0)
	v_mfma_f32_32x32x16_bf16 v[32:47], v[4:7], v[0:3], 0
	ds_read_b128 v[4:7], v128 offset:9248
	s_waitcnt lgkmcnt(0)
	v_mfma_f32_32x32x16_bf16 v[32:47], v[4:7], v[132:135], v[32:47]
	ds_read_b128 v[4:7], v128 offset:9280
	s_waitcnt lgkmcnt(0)
	v_mfma_f32_32x32x16_bf16 v[32:47], v[4:7], v[136:139], v[32:47]
	ds_read_b128 v[4:7], v128 offset:9312
	s_waitcnt lgkmcnt(0)
	v_mfma_f32_32x32x16_bf16 v[32:47], v[4:7], v[148:151], v[32:47]
	ds_read_b128 v[4:7], v128 offset:13824
	s_waitcnt lgkmcnt(0)
	v_mfma_f32_32x32x16_bf16 v[16:31], v[4:7], v[0:3], 0
	ds_read_b128 v[4:7], v128 offset:13856
	s_waitcnt lgkmcnt(0)
	v_mfma_f32_32x32x16_bf16 v[16:31], v[4:7], v[132:135], v[16:31]
	ds_read_b128 v[4:7], v128 offset:13888
	s_waitcnt lgkmcnt(0)
	v_mfma_f32_32x32x16_bf16 v[16:31], v[4:7], v[136:139], v[16:31]
	ds_read_b128 v[4:7], v128 offset:13920
	s_waitcnt lgkmcnt(0)
	v_mfma_f32_32x32x16_bf16 v[16:31], v[4:7], v[148:151], v[16:31]
	ds_read_b128 v[4:7], v128 offset:18432
	s_waitcnt lgkmcnt(0)
	v_mfma_f32_32x32x16_bf16 v[0:15], v[4:7], v[0:3], 0
	v_mfma_f32_32x32x16_bf16 v[0:15], v[152:155], v[132:135], v[0:15]
	ds_read_b128 v[132:135], v128 offset:18496
	v_add_u32_e32 v153, s16, v113
	s_waitcnt lgkmcnt(0)
	v_mfma_f32_32x32x16_bf16 v[0:15], v[132:135], v[136:139], v[0:15]
	ds_read_b128 v[132:135], v128 offset:18528
	v_or_b32_e32 v128, v130, v146
	v_cmp_lt_i32_e64 s[0:1], s92, v128
	s_or_b64 s[0:1], s[8:9], s[0:1]
	s_waitcnt lgkmcnt(0)
	v_mfma_f32_32x32x16_bf16 v[0:15], v[132:135], v[148:151], v[0:15]
	v_sub_u32_e32 v132, v129, v128
	v_cmp_gt_u32_e32 vcc, s33, v132
	s_and_b64 vcc, s[0:1], vcc
	v_sub_u32_e32 v132, v128, v129
	v_cmp_lt_i32_e64 s[0:1], s24, v128
	v_cndmask_b32_e32 v64, v205, v64, vcc
	v_cmp_lt_u32_e32 vcc, s22, v132
	s_or_b64 s[0:1], s[8:9], s[0:1]
	v_or_b32_e32 v133, v130, v81
	s_and_b64 vcc, s[0:1], vcc
	v_sub_u32_e32 v134, v129, v133
	v_cmp_lt_i32_e64 s[0:1], s92, v133
	v_cndmask_b32_e32 v65, v205, v65, vcc
	v_cmp_gt_u32_e32 vcc, s33, v134
	s_or_b64 s[0:1], s[8:9], s[0:1]
	v_or_b32_e32 v133, v130, v83
	s_and_b64 vcc, s[0:1], vcc
	v_sub_u32_e32 v134, v129, v133
	v_cmp_lt_i32_e64 s[0:1], s92, v133
	v_cndmask_b32_e32 v66, v205, v66, vcc
	v_cmp_gt_u32_e32 vcc, s33, v134
	s_or_b64 s[0:1], s[8:9], s[0:1]
	v_or_b32_e32 v133, v130, v99
	s_and_b64 vcc, s[0:1], vcc
	v_sub_u32_e32 v134, v129, v133
	v_cmp_lt_i32_e64 s[0:1], s92, v133
	v_cndmask_b32_e32 v67, v205, v67, vcc
	v_cmp_gt_u32_e32 vcc, s33, v134
	s_or_b64 s[0:1], s[8:9], s[0:1]
	v_or_b32_e32 v133, v130, v100
	s_and_b64 vcc, s[0:1], vcc
	v_sub_u32_e32 v134, v129, v133
	v_cmp_lt_i32_e64 s[0:1], s92, v133
	v_cndmask_b32_e32 v68, v205, v68, vcc
	v_cmp_gt_u32_e32 vcc, s33, v134
	s_or_b64 s[0:1], s[8:9], s[0:1]
	v_or_b32_e32 v133, v130, v101
	s_and_b64 vcc, s[0:1], vcc
	v_sub_u32_e32 v134, v129, v133
	v_cmp_lt_i32_e64 s[0:1], s92, v133
	v_cndmask_b32_e32 v69, v205, v69, vcc
	v_cmp_gt_u32_e32 vcc, s33, v134
	s_or_b64 s[0:1], s[8:9], s[0:1]
	v_or_b32_e32 v133, v130, v102
	s_and_b64 vcc, s[0:1], vcc
	v_sub_u32_e32 v134, v129, v133
	v_cmp_lt_i32_e64 s[0:1], s92, v133
	v_cndmask_b32_e32 v70, v205, v70, vcc
	v_cmp_gt_u32_e32 vcc, s33, v134
	s_or_b64 s[0:1], s[8:9], s[0:1]
	v_or_b32_e32 v133, v130, v103
	s_and_b64 vcc, s[0:1], vcc
	v_sub_u32_e32 v134, v129, v133
	v_cmp_lt_i32_e64 s[0:1], s92, v133
	v_cndmask_b32_e32 v71, v205, v71, vcc
	v_cmp_gt_u32_e32 vcc, s33, v134
	s_or_b64 s[0:1], s[8:9], s[0:1]
	v_or_b32_e32 v133, v130, v104
	s_and_b64 vcc, s[0:1], vcc
	v_sub_u32_e32 v134, v129, v133
	v_cmp_lt_i32_e64 s[0:1], s92, v133
	v_cndmask_b32_e32 v72, v205, v72, vcc
	v_cmp_gt_u32_e32 vcc, s33, v134
	s_or_b64 s[0:1], s[8:9], s[0:1]
	v_or_b32_e32 v133, v130, v105
	s_and_b64 vcc, s[0:1], vcc
	v_sub_u32_e32 v134, v129, v133
	v_cmp_lt_i32_e64 s[0:1], s92, v133
	v_cndmask_b32_e32 v73, v205, v73, vcc
	v_cmp_gt_u32_e32 vcc, s33, v134
	s_or_b64 s[0:1], s[8:9], s[0:1]
	v_or_b32_e32 v133, v130, v106
	s_and_b64 vcc, s[0:1], vcc
	v_sub_u32_e32 v134, v129, v133
	v_cmp_lt_i32_e64 s[0:1], s92, v133
	v_cndmask_b32_e32 v74, v205, v74, vcc
	v_cmp_gt_u32_e32 vcc, s33, v134
	s_or_b64 s[0:1], s[8:9], s[0:1]
	v_or_b32_e32 v133, v130, v107
	s_and_b64 vcc, s[0:1], vcc
	v_sub_u32_e32 v134, v129, v133
	v_cmp_lt_i32_e64 s[0:1], s92, v133
	v_cndmask_b32_e32 v75, v205, v75, vcc
	v_cmp_gt_u32_e32 vcc, s33, v134
	s_or_b64 s[0:1], s[8:9], s[0:1]
	v_or_b32_e32 v133, v130, v108
	s_and_b64 vcc, s[0:1], vcc
	v_sub_u32_e32 v134, v129, v133
	v_cmp_lt_i32_e64 s[0:1], s92, v133
	v_max3_f32 v132, v64, s20, v65
	v_cndmask_b32_e32 v76, v205, v76, vcc
	v_cmp_gt_u32_e32 vcc, s33, v134
	s_or_b64 s[0:1], s[8:9], s[0:1]
	v_or_b32_e32 v133, v130, v109
	v_max3_f32 v132, v132, v66, v67
	s_and_b64 vcc, s[0:1], vcc
	v_sub_u32_e32 v134, v129, v133
	v_cmp_lt_i32_e64 s[0:1], s92, v133
	v_max3_f32 v132, v132, v68, v69
	v_cndmask_b32_e32 v77, v205, v77, vcc
	v_cmp_gt_u32_e32 vcc, s33, v134
	s_or_b64 s[0:1], s[8:9], s[0:1]
	v_or_b32_e32 v130, v130, v110
	v_max3_f32 v132, v132, v70, v71
	s_and_b64 vcc, s[0:1], vcc
	v_sub_u32_e32 v133, v129, v130
	v_cmp_lt_i32_e64 s[0:1], s92, v130
	v_max3_f32 v132, v132, v72, v73
	v_cndmask_b32_e32 v78, v205, v78, vcc
	v_cmp_gt_u32_e32 vcc, s33, v133
	s_or_b64 s[0:1], s[8:9], s[0:1]
	v_max3_f32 v132, v132, v74, v75
	s_and_b64 vcc, s[0:1], vcc
	v_max3_f32 v132, v132, v76, v77
	v_cndmask_b32_e32 v79, v205, v79, vcc
	v_max3_f32 v130, v132, v78, v79
	s_cmp_eq_u64 s[8:9], 0
	s_cbranch_scc1 .Lmy_am_slow
; __device__ __forceinline__ float xor32_max(float v) { float a = v, b = v; asm volatile("s_nop 1\n\tv_permlane32_swap_b32 %0, %1\n\ts_nop 1" : "+v"(a), "+v"(b)); return fmaxf(a, b); }
; __device__ __forceinline__ void attn_prompt_unit(unsigned char* lds, const bf16_t* Q, const bf16_t* Kb, const bf16_t* Vb, bf16_t* MIX, const float* sinks, int unit, int tid) {
;     ...
; #pragma unroll
;         for (int kb = 0; kb < 5; ++kb)
; #pragma unroll
;             for (int r = 0; r < 16; ++r) { const int kj = q0 + 32 * kb + (r & 3) + 8 * (r >> 2) + 4 * hi; const int rel = 128 + qi - kj;
;                 const bool ok = (rel >= 0) && (rel < 128) && (nb > 0 || kj >= 128);
;                 const float s = ok ? S[kb][r] : -1e30f; S[kb][r] = s; mx = fmaxf(mx, s); }
;         mx = fmaxf(xor32_max(mx), sink);
	v_max3_f32 v130, v130, v48, v49
	v_max3_f32 v130, v130, v50, v51
	v_max3_f32 v130, v130, v52, v53
	v_max3_f32 v130, v130, v54, v55
	v_max3_f32 v130, v130, v56, v57
	v_max3_f32 v130, v130, v58, v59
	v_max3_f32 v130, v130, v60, v61
	v_max3_f32 v132, v130, v62, v63
	v_max3_f32 v132, v132, v32, v33
	v_max3_f32 v132, v132, v34, v35
	v_max3_f32 v132, v132, v36, v37
	v_max3_f32 v132, v132, v38, v39
	v_max3_f32 v132, v132, v40, v41
	v_max3_f32 v132, v132, v42, v43
	v_max3_f32 v132, v132, v44, v45
	v_max3_f32 v133, v132, v46, v47
	s_branch .Lmy_am_join
.Lmy_am_slow:
	v_add_u32_e32 v132, s16, v117
	v_or_b32_e32 v133, v132, v146
	v_sub_u32_e32 v134, v129, v133
	v_cmp_lt_i32_e64 s[0:1], s92, v133
	v_cmp_gt_u32_e32 vcc, s33, v134
	s_or_b64 s[0:1], s[8:9], s[0:1]
	s_and_b64 vcc, vcc, s[0:1]
	v_sub_u32_e32 v134, v133, v129
	v_cmp_lt_i32_e64 s[0:1], s24, v133
	v_cndmask_b32_e32 v48, v205, v48, vcc
	v_cmp_lt_u32_e32 vcc, s22, v134
	s_or_b64 s[0:1], s[8:9], s[0:1]
	v_or_b32_e32 v133, v132, v81
	s_and_b64 vcc, vcc, s[0:1]
	v_sub_u32_e32 v134, v129, v133
	v_cmp_lt_i32_e64 s[0:1], s92, v133
	v_cndmask_b32_e32 v49, v205, v49, vcc
	v_cmp_gt_u32_e32 vcc, s33, v134
	s_or_b64 s[0:1], s[8:9], s[0:1]
	v_or_b32_e32 v133, v132, v83
	s_and_b64 vcc, vcc, s[0:1]
	v_sub_u32_e32 v134, v129, v133
	v_cmp_lt_i32_e64 s[0:1], s92, v133
	v_cndmask_b32_e32 v50, v205, v50, vcc
	v_cmp_gt_u32_e32 vcc, s33, v134
	s_or_b64 s[0:1], s[8:9], s[0:1]
	v_or_b32_e32 v133, v132, v99
	s_and_b64 vcc, vcc, s[0:1]
	v_sub_u32_e32 v134, v129, v133
	v_cmp_lt_i32_e64 s[0:1], s92, v133
	v_cndmask_b32_e32 v51, v205, v51, vcc
	v_cmp_gt_u32_e32 vcc, s33, v134
	s_or_b64 s[0:1], s[8:9], s[0:1]
	v_or_b32_e32 v133, v132, v100
	s_and_b64 vcc, vcc, s[0:1]
	v_sub_u32_e32 v134, v129, v133
	v_cmp_lt_i32_e64 s[0:1], s92, v133
	v_cndmask_b32_e32 v52, v205, v52, vcc
	v_cmp_gt_u32_e32 vcc, s33, v134
	s_or_b64 s[0:1], s[8:9], s[0:1]
	v_or_b32_e32 v133, v132, v101
	s_and_b64 vcc, vcc, s[0:1]
	v_sub_u32_e32 v134, v129, v133
	v_cmp_lt_i32_e64 s[0:1], s92, v133
	v_cndmask_b32_e32 v53, v205, v53, vcc
	v_cmp_gt_u32_e32 vcc, s33, v134
	s_or_b64 s[0:1], s[8:9], s[0:1]
	v_or_b32_e32 v133, v132, v102
	s_and_b64 vcc, vcc, s[0:1]
	v_sub_u32_e32 v134, v129, v133
	v_cmp_lt_i32_e64 s[0:1], s92, v133
	v_cndmask_b32_e32 v54, v205, v54, vcc
	v_cmp_gt_u32_e32 vcc, s33, v134
	s_or_b64 s[0:1], s[8:9], s[0:1]
	v_or_b32_e32 v133, v132, v103
	s_and_b64 vcc, vcc, s[0:1]
	v_sub_u32_e32 v134, v129, v133
	v_cmp_lt_i32_e64 s[0:1], s92, v133
	v_cndmask_b32_e32 v55, v205, v55, vcc
	v_cmp_gt_u32_e32 vcc, s33, v134
	s_or_b64 s[0:1], s[8:9], s[0:1]
	v_or_b32_e32 v133, v132, v104
	s_and_b64 vcc, vcc, s[0:1]
	v_sub_u32_e32 v134, v129, v133
	v_cmp_lt_i32_e64 s[0:1], s92, v133
	v_cndmask_b32_e32 v56, v205, v56, vcc
	v_cmp_gt_u32_e32 vcc, s33, v134
	s_or_b64 s[0:1], s[8:9], s[0:1]
	v_or_b32_e32 v133, v132, v105
	s_and_b64 vcc, vcc, s[0:1]
	v_sub_u32_e32 v134, v129, v133
	v_cmp_lt_i32_e64 s[0:1], s92, v133
	v_cndmask_b32_e32 v57, v205, v57, vcc
	v_cmp_gt_u32_e32 vcc, s33, v134
	s_or_b64 s[0:1], s[8:9], s[0:1]
	v_or_b32_e32 v133, v132, v106
	s_and_b64 vcc, vcc, s[0:1]
	v_sub_u32_e32 v134, v129, v133
	v_cmp_lt_i32_e64 s[0:1], s92, v133
	v_cndmask_b32_e32 v58, v205, v58, vcc
	v_cmp_gt_u32_e32 vcc, s33, v134
	s_or_b64 s[0:1], s[8:9], s[0:1]
	v_or_b32_e32 v133, v132, v107
	s_and_b64 vcc, vcc, s[0:1]
	v_sub_u32_e32 v134, v129, v133
	v_cmp_lt_i32_e64 s[0:1], s92, v133
	v_cndmask_b32_e32 v59, v205, v59, vcc
	v_cmp_gt_u32_e32 vcc, s33, v134
	s_or_b64 s[0:1], s[8:9], s[0:1]
	v_or_b32_e32 v133, v132, v108
	s_and_b64 vcc, vcc, s[0:1]
	v_sub_u32_e32 v134, v129, v133
	v_cmp_lt_i32_e64 s[0:1], s92, v133
	v_max3_f32 v130, v130, v48, v49
	v_cndmask_b32_e32 v60, v205, v60, vcc
	v_cmp_gt_u32_e32 vcc, s33, v134
	s_or_b64 s[0:1], s[8:9], s[0:1]
	v_or_b32_e32 v133, v132, v109
	v_max3_f32 v130, v130, v50, v51
	s_and_b64 vcc, vcc, s[0:1]
	v_sub_u32_e32 v134, v129, v133
	v_cmp_lt_i32_e64 s[0:1], s92, v133
	v_max3_f32 v130, v130, v52, v53
	v_cndmask_b32_e32 v61, v205, v61, vcc
	v_cmp_gt_u32_e32 vcc, s33, v134
	s_or_b64 s[0:1], s[8:9], s[0:1]
	v_or_b32_e32 v132, v132, v110
	v_max3_f32 v130, v130, v54, v55
	s_and_b64 vcc, vcc, s[0:1]
	v_sub_u32_e32 v133, v129, v132
	v_cmp_lt_i32_e64 s[0:1], s92, v132
	v_max3_f32 v130, v130, v56, v57
	v_cndmask_b32_e32 v62, v205, v62, vcc
	v_cmp_gt_u32_e32 vcc, s33, v133
	s_or_b64 s[0:1], s[8:9], s[0:1]
	v_max3_f32 v130, v130, v58, v59
	s_and_b64 vcc, vcc, s[0:1]
	v_max3_f32 v130, v130, v60, v61
	v_cndmask_b32_e32 v63, v205, v63, vcc
	v_max3_f32 v132, v130, v62, v63
	v_or_b32_e32 v130, s16, v111
	v_or_b32_e32 v133, v130, v146
	v_sub_u32_e32 v134, v129, v133
	v_cmp_lt_i32_e64 s[0:1], s92, v133
	v_cmp_gt_u32_e32 vcc, s33, v134
	s_or_b64 s[0:1], s[8:9], s[0:1]
	s_and_b64 vcc, s[0:1], vcc
	v_sub_u32_e32 v134, v133, v129
	v_cmp_lt_i32_e64 s[0:1], s24, v133
	v_cndmask_b32_e32 v32, v205, v32, vcc
	v_cmp_lt_u32_e32 vcc, s22, v134
	s_or_b64 s[0:1], s[8:9], s[0:1]
	v_or_b32_e32 v133, v130, v81
	s_and_b64 vcc, s[0:1], vcc
	v_sub_u32_e32 v134, v129, v133
	v_cmp_lt_i32_e64 s[0:1], s92, v133
	v_cndmask_b32_e32 v33, v205, v33, vcc
	v_cmp_gt_u32_e32 vcc, s33, v134
	s_or_b64 s[0:1], s[8:9], s[0:1]
	v_or_b32_e32 v133, v130, v83
	s_and_b64 vcc, s[0:1], vcc
	v_sub_u32_e32 v134, v129, v133
	v_cmp_lt_i32_e64 s[0:1], s92, v133
	v_cndmask_b32_e32 v34, v205, v34, vcc
	v_cmp_gt_u32_e32 vcc, s33, v134
	s_or_b64 s[0:1], s[8:9], s[0:1]
	v_or_b32_e32 v133, v130, v99
	s_and_b64 vcc, s[0:1], vcc
	v_sub_u32_e32 v134, v129, v133
	v_cmp_lt_i32_e64 s[0:1], s92, v133
	v_cndmask_b32_e32 v35, v205, v35, vcc
	v_cmp_gt_u32_e32 vcc, s33, v134
	s_or_b64 s[0:1], s[8:9], s[0:1]
; __device__ __forceinline__ float xor32_max(float v) { float a = v, b = v; asm volatile("s_nop 1\n\tv_permlane32_swap_b32 %0, %1\n\ts_nop 1" : "+v"(a), "+v"(b)); return fmaxf(a, b); }
; __device__ __forceinline__ void attn_prompt_unit(unsigned char* lds, const bf16_t* Q, const bf16_t* Kb, const bf16_t* Vb, bf16_t* MIX, const float* sinks, int unit, int tid) {
;     ...
; #pragma unroll
;         for (int kb = 0; kb < 5; ++kb)
; #pragma unroll
;             for (int r = 0; r < 16; ++r) { const int kj = q0 + 32 * kb + (r & 3) + 8 * (r >> 2) + 4 * hi; const int rel = 128 + qi - kj;
;                 const bool ok = (rel >= 0) && (rel < 128) && (nb > 0 || kj >= 128);
;                 const float s = ok ? S[kb][r] : -1e30f; S[kb][r] = s; mx = fmaxf(mx, s); }
;         mx = fmaxf(xor32_max(mx), sink);
	v_or_b32_e32 v133, v130, v100
	s_and_b64 vcc, s[0:1], vcc
	v_sub_u32_e32 v134, v129, v133
	v_cmp_lt_i32_e64 s[0:1], s92, v133
	v_cndmask_b32_e32 v36, v205, v36, vcc
	v_cmp_gt_u32_e32 vcc, s33, v134
	s_or_b64 s[0:1], s[8:9], s[0:1]
	v_or_b32_e32 v133, v130, v101
	s_and_b64 vcc, s[0:1], vcc
	v_sub_u32_e32 v134, v129, v133
	v_cmp_lt_i32_e64 s[0:1], s92, v133
	v_cndmask_b32_e32 v37, v205, v37, vcc
	v_cmp_gt_u32_e32 vcc, s33, v134
	s_or_b64 s[0:1], s[8:9], s[0:1]
	v_or_b32_e32 v133, v130, v102
	s_and_b64 vcc, s[0:1], vcc
	v_sub_u32_e32 v134, v129, v133
	v_cmp_lt_i32_e64 s[0:1], s92, v133
	v_cndmask_b32_e32 v38, v205, v38, vcc
	v_cmp_gt_u32_e32 vcc, s33, v134
	s_or_b64 s[0:1], s[8:9], s[0:1]
	v_or_b32_e32 v133, v130, v103
	s_and_b64 vcc, s[0:1], vcc
	v_sub_u32_e32 v134, v129, v133
	v_cmp_lt_i32_e64 s[0:1], s92, v133
	v_cndmask_b32_e32 v39, v205, v39, vcc
	v_cmp_gt_u32_e32 vcc, s33, v134
	s_or_b64 s[0:1], s[8:9], s[0:1]
	v_or_b32_e32 v133, v130, v104
	s_and_b64 vcc, s[0:1], vcc
	v_sub_u32_e32 v134, v129, v133
	v_cmp_lt_i32_e64 s[0:1], s92, v133
	v_cndmask_b32_e32 v40, v205, v40, vcc
	v_cmp_gt_u32_e32 vcc, s33, v134
	s_or_b64 s[0:1], s[8:9], s[0:1]
	v_or_b32_e32 v133, v130, v105
	s_and_b64 vcc, s[0:1], vcc
	v_sub_u32_e32 v134, v129, v133
	v_cmp_lt_i32_e64 s[0:1], s92, v133
	v_cndmask_b32_e32 v41, v205, v41, vcc
	v_cmp_gt_u32_e32 vcc, s33, v134
	s_or_b64 s[0:1], s[8:9], s[0:1]
	v_or_b32_e32 v133, v130, v106
	s_and_b64 vcc, s[0:1], vcc
	v_sub_u32_e32 v134, v129, v133
	v_cmp_lt_i32_e64 s[0:1], s92, v133
	v_cndmask_b32_e32 v42, v205, v42, vcc
	v_cmp_gt_u32_e32 vcc, s33, v134
	s_or_b64 s[0:1], s[8:9], s[0:1]
	v_or_b32_e32 v133, v130, v107
	s_and_b64 vcc, s[0:1], vcc
	v_sub_u32_e32 v134, v129, v133
	v_cmp_lt_i32_e64 s[0:1], s92, v133
	v_cndmask_b32_e32 v43, v205, v43, vcc
	v_cmp_gt_u32_e32 vcc, s33, v134
	s_or_b64 s[0:1], s[8:9], s[0:1]
	v_or_b32_e32 v133, v130, v108
	s_and_b64 vcc, s[0:1], vcc
	v_sub_u32_e32 v134, v129, v133
	v_cmp_lt_i32_e64 s[0:1], s92, v133
	v_max3_f32 v132, v132, v32, v33
	v_cndmask_b32_e32 v44, v205, v44, vcc
	v_cmp_gt_u32_e32 vcc, s33, v134
	s_or_b64 s[0:1], s[8:9], s[0:1]
	v_or_b32_e32 v133, v130, v109
	v_max3_f32 v132, v132, v34, v35
	s_and_b64 vcc, s[0:1], vcc
	v_sub_u32_e32 v134, v129, v133
	v_cmp_lt_i32_e64 s[0:1], s92, v133
	v_max3_f32 v132, v132, v36, v37
	v_cndmask_b32_e32 v45, v205, v45, vcc
	v_cmp_gt_u32_e32 vcc, s33, v134
	s_or_b64 s[0:1], s[8:9], s[0:1]
	v_or_b32_e32 v130, v130, v110
	v_max3_f32 v132, v132, v38, v39
	s_and_b64 vcc, s[0:1], vcc
	v_sub_u32_e32 v133, v129, v130
	v_cmp_lt_i32_e64 s[0:1], s92, v130
	v_max3_f32 v132, v132, v40, v41
	v_cndmask_b32_e32 v46, v205, v46, vcc
	v_cmp_gt_u32_e32 vcc, s33, v133
	s_or_b64 s[0:1], s[8:9], s[0:1]
	v_max3_f32 v132, v132, v42, v43
	s_and_b64 vcc, s[0:1], vcc
	v_max3_f32 v132, v132, v44, v45
	v_cndmask_b32_e32 v47, v205, v47, vcc
	v_max3_f32 v133, v132, v46, v47
.Lmy_am_join:
	v_or_b32_e32 v132, v153, v146
	v_sub_u32_e32 v130, v129, v132
	v_cmp_lt_i32_e64 s[0:1], s92, v132
	v_cmp_gt_u32_e32 vcc, s33, v130
	s_or_b64 s[0:1], s[8:9], s[0:1]
	s_and_b64 vcc, s[0:1], vcc
	v_cndmask_b32_e32 v130, v205, v16, vcc
	v_sub_u32_e32 v16, v132, v129
	v_cmp_lt_i32_e64 s[0:1], s24, v132
	v_cmp_lt_u32_e32 vcc, s22, v16
	s_or_b64 s[0:1], s[8:9], s[0:1]
	s_and_b64 vcc, s[0:1], vcc
	v_cndmask_b32_e32 v132, v205, v17, vcc
	v_or_b32_e32 v17, v153, v81
	v_max3_f32 v16, v133, v130, v132
	v_sub_u32_e32 v133, v129, v17
	v_cmp_lt_i32_e64 s[0:1], s92, v17
	v_cmp_gt_u32_e32 vcc, s33, v133
	s_or_b64 s[0:1], s[8:9], s[0:1]
	s_and_b64 vcc, s[0:1], vcc
	v_or_b32_e32 v17, v153, v83
	v_cndmask_b32_e32 v133, v205, v18, vcc
	v_sub_u32_e32 v18, v129, v17
	v_cmp_lt_i32_e64 s[0:1], s92, v17
	v_cmp_gt_u32_e32 vcc, s33, v18
	s_or_b64 s[0:1], s[8:9], s[0:1]
	v_or_b32_e32 v17, v153, v99
	s_and_b64 vcc, s[0:1], vcc
	v_sub_u32_e32 v18, v129, v17
	v_cmp_lt_i32_e64 s[0:1], s92, v17
	v_cndmask_b32_e32 v134, v205, v19, vcc
	v_cmp_gt_u32_e32 vcc, s33, v18
	s_or_b64 s[0:1], s[8:9], s[0:1]
	v_or_b32_e32 v17, v153, v100
	s_and_b64 vcc, s[0:1], vcc
	v_sub_u32_e32 v18, v129, v17
	v_cmp_lt_i32_e64 s[0:1], s92, v17
	v_cndmask_b32_e32 v135, v205, v20, vcc
	v_cmp_gt_u32_e32 vcc, s33, v18
	s_or_b64 s[0:1], s[8:9], s[0:1]
	v_or_b32_e32 v17, v153, v101
	s_and_b64 vcc, s[0:1], vcc
	v_sub_u32_e32 v18, v129, v17
	v_cmp_lt_i32_e64 s[0:1], s92, v17
	v_cndmask_b32_e32 v136, v205, v21, vcc
	v_cmp_gt_u32_e32 vcc, s33, v18
	s_or_b64 s[0:1], s[8:9], s[0:1]
	v_or_b32_e32 v17, v153, v102
	s_and_b64 vcc, s[0:1], vcc
	v_sub_u32_e32 v18, v129, v17
	v_cmp_lt_i32_e64 s[0:1], s92, v17
	v_cndmask_b32_e32 v137, v205, v22, vcc
	v_cmp_gt_u32_e32 vcc, s33, v18
	s_or_b64 s[0:1], s[8:9], s[0:1]
	v_or_b32_e32 v17, v153, v103
	s_and_b64 vcc, s[0:1], vcc
	v_sub_u32_e32 v18, v129, v17
	v_cmp_lt_i32_e64 s[0:1], s92, v17
	v_cndmask_b32_e32 v138, v205, v23, vcc
	v_cmp_gt_u32_e32 vcc, s33, v18
	s_or_b64 s[0:1], s[8:9], s[0:1]
	v_or_b32_e32 v17, v153, v104
	s_and_b64 vcc, s[0:1], vcc
	v_sub_u32_e32 v18, v129, v17
	v_cmp_lt_i32_e64 s[0:1], s92, v17
	v_cndmask_b32_e32 v139, v205, v24, vcc
	v_cmp_gt_u32_e32 vcc, s33, v18
	s_or_b64 s[0:1], s[8:9], s[0:1]
	v_or_b32_e32 v17, v153, v105
	s_and_b64 vcc, s[0:1], vcc
	v_sub_u32_e32 v18, v129, v17
	v_cmp_lt_i32_e64 s[0:1], s92, v17
	v_cndmask_b32_e32 v148, v205, v25, vcc
	v_cmp_gt_u32_e32 vcc, s33, v18
	s_or_b64 s[0:1], s[8:9], s[0:1]
	v_or_b32_e32 v17, v153, v106
	s_and_b64 vcc, s[0:1], vcc
	v_sub_u32_e32 v18, v129, v17
	v_cmp_lt_i32_e64 s[0:1], s92, v17
	v_cndmask_b32_e32 v149, v205, v26, vcc
	v_cmp_gt_u32_e32 vcc, s33, v18
	s_or_b64 s[0:1], s[8:9], s[0:1]
	v_or_b32_e32 v17, v153, v107
	s_and_b64 vcc, s[0:1], vcc
; __device__ __forceinline__ float xor32_sum(float v) { float a = v, b = v; asm volatile("s_nop 1\n\tv_permlane32_swap_b32 %0, %1\n\ts_nop 1" : "+v"(a), "+v"(b)); return a + b; }
; __device__ __forceinline__ float xor32_max(float v) { float a = v, b = v; asm volatile("s_nop 1\n\tv_permlane32_swap_b32 %0, %1\n\ts_nop 1" : "+v"(a), "+v"(b)); return fmaxf(a, b); }
; __device__ __forceinline__ void attn_prompt_unit(unsigned char* lds, const bf16_t* Q, const bf16_t* Kb, const bf16_t* Vb, bf16_t* MIX, const float* sinks, int unit, int tid) {
;     ...
; #pragma unroll
;         for (int kb = 0; kb < 5; ++kb)
; #pragma unroll
;             for (int r = 0; r < 16; ++r) { const int kj = q0 + 32 * kb + (r & 3) + 8 * (r >> 2) + 4 * hi; const int rel = 128 + qi - kj;
;                 const bool ok = (rel >= 0) && (rel < 128) && (nb > 0 || kj >= 128);
;                 const float s = ok ? S[kb][r] : -1e30f; S[kb][r] = s; mx = fmaxf(mx, s); }
;         mx = fmaxf(xor32_max(mx), sink);
;         float sum = 0.f;
; #pragma unroll
;         for (int kb = 0; kb < 5; ++kb)
; #pragma unroll
;             for (int r = 0; r < 16; ++r) { const float e = __expf(S[kb][r] - mx); S[kb][r] = e; sum += e; }
;         sum = xor32_sum(sum) + __expf(sink - mx);
	v_sub_u32_e32 v18, v129, v17
	v_cmp_lt_i32_e64 s[0:1], s92, v17
	v_cndmask_b32_e32 v150, v205, v27, vcc
	v_cmp_gt_u32_e32 vcc, s33, v18
	s_or_b64 s[0:1], s[8:9], s[0:1]
	v_or_b32_e32 v17, v153, v108
	s_and_b64 vcc, s[0:1], vcc
	v_sub_u32_e32 v18, v129, v17
	v_cmp_lt_i32_e64 s[0:1], s92, v17
	v_cndmask_b32_e32 v151, v205, v28, vcc
	v_cmp_gt_u32_e32 vcc, s33, v18
	s_or_b64 s[0:1], s[8:9], s[0:1]
	v_or_b32_e32 v17, v153, v109
	s_and_b64 vcc, s[0:1], vcc
	v_sub_u32_e32 v18, v129, v17
	v_cmp_lt_i32_e64 s[0:1], s92, v17
	v_cndmask_b32_e32 v152, v205, v29, vcc
	v_cmp_gt_u32_e32 vcc, s33, v18
	s_or_b64 s[0:1], s[8:9], s[0:1]
	v_or_b32_e32 v17, v153, v110
	s_and_b64 vcc, s[0:1], vcc
	v_sub_u32_e32 v18, v129, v17
	v_cmp_lt_i32_e64 s[0:1], s92, v17
	v_or_b32_e32 v17, s16, v116
	v_cndmask_b32_e32 v30, v205, v30, vcc
	v_cmp_gt_u32_e32 vcc, s33, v18
	s_or_b64 s[0:1], s[8:9], s[0:1]
	v_or_b32_e32 v18, v17, v146
	v_max3_f32 v16, v16, v133, v134
	s_and_b64 vcc, s[0:1], vcc
	v_sub_u32_e32 v19, v129, v18
	v_cmp_lt_i32_e64 s[0:1], s92, v18
	v_max3_f32 v16, v16, v135, v136
	v_cndmask_b32_e32 v31, v205, v31, vcc
	v_cmp_gt_u32_e32 vcc, s33, v19
	s_or_b64 s[0:1], s[8:9], s[0:1]
	v_max3_f32 v16, v16, v137, v138
	s_and_b64 vcc, s[0:1], vcc
	v_max3_f32 v16, v16, v139, v148
	v_cndmask_b32_e32 v153, v205, v0, vcc
	v_sub_u32_e32 v0, v18, v129
	v_cmp_lt_i32_e64 s[0:1], s24, v18
	v_max3_f32 v16, v16, v149, v150
	v_cmp_lt_u32_e32 vcc, s22, v0
	s_or_b64 s[0:1], s[8:9], s[0:1]
	v_max3_f32 v16, v16, v151, v152
	s_and_b64 vcc, s[0:1], vcc
	v_max3_f32 v16, v16, v30, v31
	v_cndmask_b32_e32 v154, v205, v1, vcc
	v_or_b32_e32 v1, v17, v81
	v_max3_f32 v0, v16, v153, v154
	v_sub_u32_e32 v16, v129, v1
	v_cmp_lt_i32_e64 s[0:1], s92, v1
	v_cmp_gt_u32_e32 vcc, s33, v16
	s_or_b64 s[0:1], s[8:9], s[0:1]
	s_and_b64 vcc, s[0:1], vcc
	v_or_b32_e32 v1, v17, v83
	v_cndmask_b32_e32 v155, v205, v2, vcc
	v_sub_u32_e32 v2, v129, v1
	v_cmp_lt_i32_e64 s[0:1], s92, v1
	v_cmp_gt_u32_e32 vcc, s33, v2
	s_or_b64 s[0:1], s[8:9], s[0:1]
	v_or_b32_e32 v1, v17, v99
	s_and_b64 vcc, s[0:1], vcc
	v_sub_u32_e32 v2, v129, v1
	v_cmp_lt_i32_e64 s[0:1], s92, v1
	v_cndmask_b32_e32 v156, v205, v3, vcc
	v_cmp_gt_u32_e32 vcc, s33, v2
	s_or_b64 s[0:1], s[8:9], s[0:1]
	v_or_b32_e32 v1, v17, v100
	s_and_b64 vcc, s[0:1], vcc
	v_sub_u32_e32 v2, v129, v1
	v_cmp_lt_i32_e64 s[0:1], s92, v1
	v_cndmask_b32_e32 v157, v205, v4, vcc
	v_cmp_gt_u32_e32 vcc, s33, v2
	s_or_b64 s[0:1], s[8:9], s[0:1]
	v_or_b32_e32 v1, v17, v101
	s_and_b64 vcc, s[0:1], vcc
	v_sub_u32_e32 v2, v129, v1
	v_cmp_lt_i32_e64 s[0:1], s92, v1
	v_cndmask_b32_e32 v158, v205, v5, vcc
	v_cmp_gt_u32_e32 vcc, s33, v2
	s_or_b64 s[0:1], s[8:9], s[0:1]
	v_or_b32_e32 v1, v17, v102
	s_and_b64 vcc, s[0:1], vcc
	v_sub_u32_e32 v2, v129, v1
	v_cmp_lt_i32_e64 s[0:1], s92, v1
	v_cndmask_b32_e32 v159, v205, v6, vcc
	v_cmp_gt_u32_e32 vcc, s33, v2
	s_or_b64 s[0:1], s[8:9], s[0:1]
	v_or_b32_e32 v1, v17, v103
	s_and_b64 vcc, s[0:1], vcc
	v_sub_u32_e32 v2, v129, v1
	v_cmp_lt_i32_e64 s[0:1], s92, v1
	v_cndmask_b32_e32 v160, v205, v7, vcc
	v_cmp_gt_u32_e32 vcc, s33, v2
	s_or_b64 s[0:1], s[8:9], s[0:1]
	v_or_b32_e32 v1, v17, v104
	s_and_b64 vcc, s[0:1], vcc
	v_sub_u32_e32 v2, v129, v1
	v_cmp_lt_i32_e64 s[0:1], s92, v1
	v_cndmask_b32_e32 v184, v205, v8, vcc
	v_cmp_gt_u32_e32 vcc, s33, v2
	s_or_b64 s[0:1], s[8:9], s[0:1]
	v_or_b32_e32 v1, v17, v105
	s_and_b64 vcc, s[0:1], vcc
	v_sub_u32_e32 v2, v129, v1
	v_cmp_lt_i32_e64 s[0:1], s92, v1
	v_cndmask_b32_e32 v185, v205, v9, vcc
	v_cmp_gt_u32_e32 vcc, s33, v2
	s_or_b64 s[0:1], s[8:9], s[0:1]
	v_or_b32_e32 v1, v17, v106
	s_and_b64 vcc, s[0:1], vcc
	v_sub_u32_e32 v2, v129, v1
	v_cmp_lt_i32_e64 s[0:1], s92, v1
	v_cndmask_b32_e32 v186, v205, v10, vcc
	v_cmp_gt_u32_e32 vcc, s33, v2
	s_or_b64 s[0:1], s[8:9], s[0:1]
	v_or_b32_e32 v1, v17, v107
	s_and_b64 vcc, s[0:1], vcc
	v_sub_u32_e32 v2, v129, v1
	v_cmp_lt_i32_e64 s[0:1], s92, v1
	v_cndmask_b32_e32 v187, v205, v11, vcc
	v_cmp_gt_u32_e32 vcc, s33, v2
	s_or_b64 s[0:1], s[8:9], s[0:1]
	v_or_b32_e32 v1, v17, v108
	s_and_b64 vcc, s[0:1], vcc
	v_sub_u32_e32 v2, v129, v1
	v_cmp_lt_i32_e64 s[0:1], s92, v1
	v_cndmask_b32_e32 v188, v205, v12, vcc
	v_cmp_gt_u32_e32 vcc, s33, v2
	s_or_b64 s[0:1], s[8:9], s[0:1]
	v_or_b32_e32 v1, v17, v109
	v_max3_f32 v0, v0, v155, v156
	s_and_b64 vcc, s[0:1], vcc
	v_sub_u32_e32 v2, v129, v1
	v_cmp_lt_i32_e64 s[0:1], s92, v1
	v_max3_f32 v0, v0, v157, v158
	v_cndmask_b32_e32 v189, v205, v13, vcc
	v_cmp_gt_u32_e32 vcc, s33, v2
	s_or_b64 s[0:1], s[8:9], s[0:1]
	v_or_b32_e32 v1, v17, v110
	v_max3_f32 v0, v0, v159, v160
	s_and_b64 vcc, s[0:1], vcc
	v_sub_u32_e32 v2, v129, v1
	v_cmp_lt_i32_e64 s[0:1], s92, v1
	v_max3_f32 v0, v0, v184, v185
	v_cndmask_b32_e32 v190, v205, v14, vcc
	v_cmp_gt_u32_e32 vcc, s33, v2
	s_or_b64 s[0:1], s[8:9], s[0:1]
	v_max3_f32 v0, v0, v186, v187
	s_and_b64 vcc, s[0:1], vcc
	v_max3_f32 v0, v0, v188, v189
	v_cndmask_b32_e32 v129, v205, v15, vcc
	v_max3_f32 v0, v0, v190, v129
	v_mov_b32_e32 v1, v0
	s_nop 1
	v_permlane32_swap_b32 v0, v1
	s_nop 1
	s_mov_b32 s16, 32
	v_max3_f32 v191, v0, v1, v127
	v_sub_f32_e32 v0, v64, v191
	v_mul_f32_e32 v0, 0x3fb8aa3b, v0
	v_sub_f32_e32 v1, v65, v191
	v_exp_f32_e32 v0, v0
	v_mul_f32_e32 v1, 0x3fb8aa3b, v1
	v_exp_f32_e32 v1, v1
	v_sub_f32_e32 v32, v32, v191
	v_add_f32_e32 v2, 0, v0
	v_mul_f32_e32 v32, 0x3fb8aa3b, v32
	v_add_f32_e32 v3, v1, v2
	v_sub_f32_e32 v2, v66, v191
	v_mul_f32_e32 v2, 0x3fb8aa3b, v2
	v_exp_f32_e32 v2, v2
	v_sub_f32_e32 v33, v33, v191
	v_mul_f32_e32 v33, 0x3fb8aa3b, v33
	v_sub_f32_e32 v31, v31, v191
	v_add_f32_e32 v4, v2, v3
	v_sub_f32_e32 v3, v67, v191
	v_mul_f32_e32 v3, 0x3fb8aa3b, v3
	v_exp_f32_e32 v3, v3
; __device__ __forceinline__ float xor32_sum(float v) { float a = v, b = v; asm volatile("s_nop 1\n\tv_permlane32_swap_b32 %0, %1\n\ts_nop 1" : "+v"(a), "+v"(b)); return a + b; }
; __device__ __forceinline__ void attn_prompt_unit(unsigned char* lds, const bf16_t* Q, const bf16_t* Kb, const bf16_t* Vb, bf16_t* MIX, const float* sinks, int unit, int tid) {
;     ...
;         float sum = 0.f;
; #pragma unroll
;         for (int kb = 0; kb < 5; ++kb)
; #pragma unroll
;             for (int r = 0; r < 16; ++r) { const float e = __expf(S[kb][r] - mx); S[kb][r] = e; sum += e; }
;         sum = xor32_sum(sum) + __expf(sink - mx);
	v_mul_f32_e32 v31, 0x3fb8aa3b, v31
	v_sub_f32_e32 v30, v30, v191
	v_mul_f32_e32 v30, 0x3fb8aa3b, v30
	v_add_f32_e32 v5, v3, v4
	v_sub_f32_e32 v4, v68, v191
	v_mul_f32_e32 v4, 0x3fb8aa3b, v4
	v_exp_f32_e32 v4, v4
	s_nop 0
	v_add_f32_e32 v6, v4, v5
	v_sub_f32_e32 v5, v69, v191
	v_mul_f32_e32 v5, 0x3fb8aa3b, v5
	v_exp_f32_e32 v5, v5
	s_nop 0
	v_add_f32_e32 v7, v5, v6
	v_sub_f32_e32 v6, v70, v191
	v_mul_f32_e32 v6, 0x3fb8aa3b, v6
	v_exp_f32_e32 v6, v6
	v_exp_f32_e32 v70, v30
	v_add_f32_e32 v8, v6, v7
	v_sub_f32_e32 v7, v71, v191
	v_mul_f32_e32 v7, 0x3fb8aa3b, v7
	v_exp_f32_e32 v7, v7
	v_exp_f32_e32 v71, v31
	v_sub_f32_e32 v31, v153, v191
	v_mul_f32_e32 v31, 0x3fb8aa3b, v31
	v_add_f32_e32 v9, v7, v8
	v_sub_f32_e32 v8, v72, v191
	v_mul_f32_e32 v8, 0x3fb8aa3b, v8
	v_exp_f32_e32 v8, v8
	v_exp_f32_e32 v72, v31
	v_sub_f32_e32 v31, v154, v191
	v_mul_f32_e32 v31, 0x3fb8aa3b, v31
	v_add_f32_e32 v10, v8, v9
	v_sub_f32_e32 v9, v73, v191
	v_mul_f32_e32 v9, 0x3fb8aa3b, v9
	v_exp_f32_e32 v9, v9
	v_exp_f32_e32 v73, v31
	v_sub_f32_e32 v31, v155, v191
	v_mul_f32_e32 v31, 0x3fb8aa3b, v31
	v_add_f32_e32 v11, v9, v10
	v_sub_f32_e32 v10, v74, v191
	v_mul_f32_e32 v10, 0x3fb8aa3b, v10
	v_exp_f32_e32 v10, v10
	v_exp_f32_e32 v74, v31
	v_sub_f32_e32 v31, v156, v191
	v_mul_f32_e32 v31, 0x3fb8aa3b, v31
	v_add_f32_e32 v12, v10, v11
	v_sub_f32_e32 v11, v75, v191
	v_mul_f32_e32 v11, 0x3fb8aa3b, v11
	v_exp_f32_e32 v11, v11
	v_exp_f32_e32 v75, v31
	v_sub_f32_e32 v31, v157, v191
	v_mul_f32_e32 v31, 0x3fb8aa3b, v31
	v_add_f32_e32 v13, v11, v12
	v_sub_f32_e32 v12, v76, v191
	v_mul_f32_e32 v12, 0x3fb8aa3b, v12
	v_exp_f32_e32 v12, v12
	v_exp_f32_e32 v76, v31
	v_sub_f32_e32 v31, v158, v191
	v_mul_f32_e32 v31, 0x3fb8aa3b, v31
	v_add_f32_e32 v14, v12, v13
	v_sub_f32_e32 v13, v77, v191
	v_mul_f32_e32 v13, 0x3fb8aa3b, v13
	v_exp_f32_e32 v13, v13
	v_exp_f32_e32 v77, v31
	v_sub_f32_e32 v31, v159, v191
	v_mul_f32_e32 v31, 0x3fb8aa3b, v31
	v_add_f32_e32 v15, v13, v14
	v_sub_f32_e32 v14, v78, v191
	v_mul_f32_e32 v14, 0x3fb8aa3b, v14
	v_exp_f32_e32 v14, v14
	v_exp_f32_e32 v78, v31
	v_sub_f32_e32 v31, v160, v191
	v_mul_f32_e32 v31, 0x3fb8aa3b, v31
	v_add_f32_e32 v16, v14, v15
	v_sub_f32_e32 v15, v79, v191
	v_mul_f32_e32 v15, 0x3fb8aa3b, v15
	v_exp_f32_e32 v15, v15
	v_exp_f32_e32 v79, v31
	v_sub_f32_e32 v31, v184, v191
	v_mul_f32_e32 v31, 0x3fb8aa3b, v31
	v_add_f32_e32 v17, v15, v16
	v_sub_f32_e32 v16, v48, v191
	v_mul_f32_e32 v16, 0x3fb8aa3b, v16
	v_exp_f32_e32 v16, v16
	s_nop 0
	v_add_f32_e32 v18, v16, v17
	v_sub_f32_e32 v17, v49, v191
	v_mul_f32_e32 v17, 0x3fb8aa3b, v17
	v_exp_f32_e32 v17, v17
	s_nop 0
	v_add_f32_e32 v19, v17, v18
	v_sub_f32_e32 v18, v50, v191
	v_mul_f32_e32 v18, 0x3fb8aa3b, v18
	v_exp_f32_e32 v18, v18
	s_nop 0
	v_add_f32_e32 v20, v18, v19
	v_sub_f32_e32 v19, v51, v191
	v_mul_f32_e32 v19, 0x3fb8aa3b, v19
	v_exp_f32_e32 v19, v19
	s_nop 0
	v_add_f32_e32 v21, v19, v20
	v_sub_f32_e32 v20, v52, v191
	v_mul_f32_e32 v20, 0x3fb8aa3b, v20
	v_exp_f32_e32 v20, v20
	s_nop 0
	v_add_f32_e32 v22, v20, v21
	v_sub_f32_e32 v21, v53, v191
	v_mul_f32_e32 v21, 0x3fb8aa3b, v21
	v_exp_f32_e32 v21, v21
	s_nop 0
	v_add_f32_e32 v23, v21, v22
	v_sub_f32_e32 v22, v54, v191
	v_mul_f32_e32 v22, 0x3fb8aa3b, v22
	v_exp_f32_e32 v22, v22
	s_nop 0
	v_add_f32_e32 v24, v22, v23
	v_sub_f32_e32 v23, v55, v191
	v_mul_f32_e32 v23, 0x3fb8aa3b, v23
	v_exp_f32_e32 v23, v23
	s_nop 0
	v_add_f32_e32 v25, v23, v24
	v_sub_f32_e32 v24, v56, v191
	v_mul_f32_e32 v24, 0x3fb8aa3b, v24
	v_exp_f32_e32 v24, v24
	s_nop 0
	v_add_f32_e32 v26, v24, v25
	v_sub_f32_e32 v25, v57, v191
	v_mul_f32_e32 v25, 0x3fb8aa3b, v25
	v_exp_f32_e32 v25, v25
	s_nop 0
	v_add_f32_e32 v27, v25, v26
	v_sub_f32_e32 v26, v58, v191
	v_mul_f32_e32 v26, 0x3fb8aa3b, v26
	v_exp_f32_e32 v26, v26
	s_nop 0
	v_add_f32_e32 v28, v26, v27
	v_sub_f32_e32 v27, v59, v191
	v_mul_f32_e32 v27, 0x3fb8aa3b, v27
	v_exp_f32_e32 v27, v27
	s_nop 0
	v_add_f32_e32 v29, v27, v28
	v_sub_f32_e32 v28, v60, v191
	v_mul_f32_e32 v28, 0x3fb8aa3b, v28
	v_exp_f32_e32 v28, v28
	s_nop 0
	v_add_f32_e32 v48, v28, v29
	v_sub_f32_e32 v29, v61, v191
	v_mul_f32_e32 v29, 0x3fb8aa3b, v29
	v_exp_f32_e32 v29, v29
	s_nop 0
	v_add_f32_e32 v49, v29, v48
	v_sub_f32_e32 v48, v62, v191
	v_mul_f32_e32 v48, 0x3fb8aa3b, v48
	v_exp_f32_e32 v48, v48
	s_nop 0
	v_add_f32_e32 v50, v48, v49
	v_sub_f32_e32 v49, v63, v191
	v_mul_f32_e32 v49, 0x3fb8aa3b, v49
	v_exp_f32_e32 v49, v49
	s_nop 0
	v_add_f32_e32 v51, v49, v50
	v_exp_f32_e32 v50, v32
	s_nop 0
	v_add_f32_e32 v32, v50, v51
	v_exp_f32_e32 v51, v33
	v_sub_f32_e32 v33, v34, v191
	v_mul_f32_e32 v33, 0x3fb8aa3b, v33
	v_exp_f32_e32 v52, v33
	v_sub_f32_e32 v33, v35, v191
	v_mul_f32_e32 v33, 0x3fb8aa3b, v33
	v_exp_f32_e32 v53, v33
	v_sub_f32_e32 v33, v36, v191
	v_mul_f32_e32 v33, 0x3fb8aa3b, v33
	v_exp_f32_e32 v54, v33
	v_sub_f32_e32 v33, v37, v191
	v_mul_f32_e32 v33, 0x3fb8aa3b, v33
	v_exp_f32_e32 v55, v33
	v_sub_f32_e32 v33, v38, v191
	v_mul_f32_e32 v33, 0x3fb8aa3b, v33
	v_exp_f32_e32 v38, v33
	v_sub_f32_e32 v33, v39, v191
	v_mul_f32_e32 v33, 0x3fb8aa3b, v33
	v_exp_f32_e32 v39, v33
	v_sub_f32_e32 v33, v40, v191
	v_mul_f32_e32 v33, 0x3fb8aa3b, v33
	v_exp_f32_e32 v40, v33
	v_sub_f32_e32 v33, v41, v191
	v_mul_f32_e32 v33, 0x3fb8aa3b, v33
	v_exp_f32_e32 v41, v33
	v_sub_f32_e32 v33, v42, v191
	v_mul_f32_e32 v33, 0x3fb8aa3b, v33
	v_exp_f32_e32 v42, v33
	v_sub_f32_e32 v33, v43, v191
	v_mul_f32_e32 v33, 0x3fb8aa3b, v33
	v_exp_f32_e32 v43, v33
	v_sub_f32_e32 v33, v44, v191
	v_mul_f32_e32 v33, 0x3fb8aa3b, v33
	v_exp_f32_e32 v44, v33
	v_sub_f32_e32 v33, v45, v191
	v_mul_f32_e32 v33, 0x3fb8aa3b, v33
	v_exp_f32_e32 v45, v33
	v_sub_f32_e32 v33, v46, v191
	v_mul_f32_e32 v33, 0x3fb8aa3b, v33
; __device__ __forceinline__ unsigned cvt_pk_bf16(float lo, float hi) { const f32x2_t v = {lo, hi}; const bf16x2_t b = __builtin_convertvector(v, bf16x2_t); return __builtin_bit_cast(unsigned, b); }
; __device__ __forceinline__ float xor32_sum(float v) { float a = v, b = v; asm volatile("s_nop 1\n\tv_permlane32_swap_b32 %0, %1\n\ts_nop 1" : "+v"(a), "+v"(b)); return a + b; }
; __device__ __forceinline__ void attn_prompt_unit(unsigned char* lds, const bf16_t* Q, const bf16_t* Kb, const bf16_t* Vb, bf16_t* MIX, const float* sinks, int unit, int tid) {
;     ...
;         float sum = 0.f;
; #pragma unroll
;         for (int kb = 0; kb < 5; ++kb)
; #pragma unroll
;             for (int r = 0; r < 16; ++r) { const float e = __expf(S[kb][r] - mx); S[kb][r] = e; sum += e; }
;         sum = xor32_sum(sum) + __expf(sink - mx);
;         const float inv = 1.0f / sum;
;         bf16x8 P[5][2];
; #pragma unroll
;         for (int kb = 0; kb < 5; ++kb)
; #pragma unroll
;             for (int sl = 0; sl < 2; ++sl) { u32x4 w;
;                 w.x = cvt_pk_bf16(S[kb][8 * sl + 0] * inv, S[kb][8 * sl + 1] * inv); w.y = cvt_pk_bf16(S[kb][8 * sl + 2] * inv, S[kb][8 * sl + 3] * inv);
;                 w.z = cvt_pk_bf16(S[kb][8 * sl + 4] * inv, S[kb][8 * sl + 5] * inv); w.w = cvt_pk_bf16(S[kb][8 * sl + 6] * inv, S[kb][8 * sl + 7] * inv);
;                 P[kb][sl] = __builtin_bit_cast(bf16x8, w); }
	v_exp_f32_e32 v46, v33
	v_sub_f32_e32 v33, v47, v191
	v_mul_f32_e32 v33, 0x3fb8aa3b, v33
	v_exp_f32_e32 v47, v33
	v_sub_f32_e32 v33, v130, v191
	v_mul_f32_e32 v33, 0x3fb8aa3b, v33
	v_exp_f32_e32 v56, v33
	v_sub_f32_e32 v33, v132, v191
	v_mul_f32_e32 v33, 0x3fb8aa3b, v33
	v_add_f32_e32 v32, v51, v32
	v_exp_f32_e32 v57, v33
	v_sub_f32_e32 v33, v133, v191
	v_add_f32_e32 v32, v52, v32
	v_mul_f32_e32 v33, 0x3fb8aa3b, v33
	v_add_f32_e32 v32, v53, v32
	v_exp_f32_e32 v58, v33
	v_sub_f32_e32 v33, v134, v191
	v_add_f32_e32 v32, v54, v32
	v_mul_f32_e32 v33, 0x3fb8aa3b, v33
	v_add_f32_e32 v32, v55, v32
	v_exp_f32_e32 v59, v33
	v_sub_f32_e32 v33, v135, v191
	v_add_f32_e32 v32, v38, v32
	v_mul_f32_e32 v33, 0x3fb8aa3b, v33
	v_add_f32_e32 v32, v39, v32
	v_exp_f32_e32 v60, v33
	v_sub_f32_e32 v33, v136, v191
	v_add_f32_e32 v32, v40, v32
	v_mul_f32_e32 v33, 0x3fb8aa3b, v33
	v_add_f32_e32 v32, v41, v32
	v_exp_f32_e32 v61, v33
	v_sub_f32_e32 v33, v137, v191
	v_add_f32_e32 v32, v42, v32
	v_mul_f32_e32 v33, 0x3fb8aa3b, v33
	v_add_f32_e32 v32, v43, v32
	v_exp_f32_e32 v62, v33
	v_sub_f32_e32 v33, v138, v191
	v_add_f32_e32 v32, v44, v32
	v_mul_f32_e32 v33, 0x3fb8aa3b, v33
	v_add_f32_e32 v32, v45, v32
	v_exp_f32_e32 v63, v33
	v_sub_f32_e32 v33, v139, v191
	v_add_f32_e32 v32, v46, v32
	v_mul_f32_e32 v33, 0x3fb8aa3b, v33
	v_add_f32_e32 v32, v47, v32
	v_exp_f32_e32 v64, v33
	v_sub_f32_e32 v33, v148, v191
	v_add_f32_e32 v32, v56, v32
	v_mul_f32_e32 v33, 0x3fb8aa3b, v33
	v_add_f32_e32 v32, v57, v32
	v_exp_f32_e32 v65, v33
	v_sub_f32_e32 v33, v149, v191
	v_add_f32_e32 v32, v58, v32
	v_mul_f32_e32 v33, 0x3fb8aa3b, v33
	v_add_f32_e32 v32, v59, v32
	v_exp_f32_e32 v66, v33
	v_sub_f32_e32 v33, v150, v191
	v_add_f32_e32 v32, v60, v32
	v_mul_f32_e32 v33, 0x3fb8aa3b, v33
	v_add_f32_e32 v32, v61, v32
	v_exp_f32_e32 v67, v33
	v_sub_f32_e32 v33, v151, v191
	v_add_f32_e32 v32, v62, v32
	v_mul_f32_e32 v33, 0x3fb8aa3b, v33
	v_add_f32_e32 v32, v63, v32
	v_exp_f32_e32 v68, v33
	v_sub_f32_e32 v33, v152, v191
	v_add_f32_e32 v32, v64, v32
	v_mul_f32_e32 v33, 0x3fb8aa3b, v33
	v_add_f32_e32 v32, v65, v32
	v_exp_f32_e32 v69, v33
	v_add_f32_e32 v32, v66, v32
	v_add_f32_e32 v32, v67, v32
	v_add_f32_e32 v32, v68, v32
	v_add_f32_e32 v32, v69, v32
	v_exp_f32_e32 v132, v31
	v_sub_f32_e32 v31, v185, v191
	v_add_f32_e32 v30, v70, v32
	v_mul_f32_e32 v31, 0x3fb8aa3b, v31
	v_add_f32_e32 v30, v71, v30
	v_exp_f32_e32 v133, v31
	v_sub_f32_e32 v31, v186, v191
	v_add_f32_e32 v30, v72, v30
	v_mul_f32_e32 v31, 0x3fb8aa3b, v31
	v_add_f32_e32 v30, v73, v30
	v_exp_f32_e32 v134, v31
	v_sub_f32_e32 v31, v187, v191
	v_add_f32_e32 v30, v74, v30
	v_mul_f32_e32 v31, 0x3fb8aa3b, v31
	v_add_f32_e32 v30, v75, v30
	v_exp_f32_e32 v135, v31
	v_sub_f32_e32 v31, v188, v191
	v_add_f32_e32 v30, v76, v30
	v_mul_f32_e32 v31, 0x3fb8aa3b, v31
	v_add_f32_e32 v30, v77, v30
	v_exp_f32_e32 v136, v31
	v_sub_f32_e32 v31, v189, v191
	v_add_f32_e32 v30, v78, v30
	v_mul_f32_e32 v31, 0x3fb8aa3b, v31
	v_add_f32_e32 v30, v79, v30
	v_exp_f32_e32 v137, v31
	v_sub_f32_e32 v31, v190, v191
	v_add_f32_e32 v30, v132, v30
	v_mul_f32_e32 v31, 0x3fb8aa3b, v31
	v_add_f32_e32 v30, v133, v30
	v_exp_f32_e32 v138, v31
	v_sub_f32_e32 v31, v129, v191
	v_add_f32_e32 v30, v134, v30
	v_mul_f32_e32 v31, 0x3fb8aa3b, v31
	v_add_f32_e32 v30, v135, v30
	v_exp_f32_e32 v139, v31
	v_add_f32_e32 v30, v136, v30
	v_add_f32_e32 v30, v137, v30
	v_add_f32_e32 v30, v138, v30
	v_add_f32_e32 v30, v139, v30
	v_mov_b32_e32 v31, v30
	s_nop 1
	v_permlane32_swap_b32 v30, v31
	s_nop 1
	s_nop 0
	v_add_f32_e32 v30, v30, v31
	v_sub_f32_e32 v31, v127, v191
	v_mul_f32_e32 v31, 0x3fb8aa3b, v31
	v_exp_f32_e32 v31, v31
	s_nop 0
	v_add_f32_e32 v30, v30, v31
	v_div_scale_f32 v31, s[0:1], v30, v30, 1.0
	v_rcp_f32_e32 v32, v31
	s_nop 0
	v_fma_f32 v33, -v31, v32, 1.0
	v_fmac_f32_e32 v32, v33, v32
	v_div_scale_f32 v33, vcc, 1.0, v30, 1.0
	v_mul_f32_e32 v34, v33, v32
	v_fma_f32 v35, -v31, v34, v33
	v_fmac_f32_e32 v34, v35, v32
	v_fma_f32 v31, -v31, v34, v33
	v_div_fmas_f32 v31, v31, v32, v34
	v_div_fixup_f32 v130, v31, v30, 1.0
	v_pk_mul_f32 v[0:1], v[0:1], v[130:131] op_sel_hi:[1,0]
	s_and_b64 vcc, exec, s[10:11]
	v_cvt_pk_bf16_f32 v30, v0, v1
	v_pk_mul_f32 v[0:1], v[2:3], v[130:131] op_sel_hi:[1,0]
	s_mov_b64 s[10:11], 0
	v_cvt_pk_bf16_f32 v31, v0, v1
	v_pk_mul_f32 v[0:1], v[4:5], v[130:131] op_sel_hi:[1,0]
	s_nop 0
	v_cvt_pk_bf16_f32 v32, v0, v1
	v_pk_mul_f32 v[0:1], v[6:7], v[130:131] op_sel_hi:[1,0]
	s_nop 0
	v_cvt_pk_bf16_f32 v33, v0, v1
	v_pk_mul_f32 v[0:1], v[8:9], v[130:131] op_sel_hi:[1,0]
	s_nop 0
	v_cvt_pk_bf16_f32 v34, v0, v1
	v_pk_mul_f32 v[0:1], v[10:11], v[130:131] op_sel_hi:[1,0]
	s_nop 0
	v_cvt_pk_bf16_f32 v35, v0, v1
	v_pk_mul_f32 v[0:1], v[12:13], v[130:131] op_sel_hi:[1,0]
	s_nop 0
	v_cvt_pk_bf16_f32 v36, v0, v1
	v_pk_mul_f32 v[0:1], v[14:15], v[130:131] op_sel_hi:[1,0]
	s_nop 0
	v_cvt_pk_bf16_f32 v37, v0, v1
	v_pk_mul_f32 v[0:1], v[16:17], v[130:131] op_sel_hi:[1,0]
	s_nop 0
	v_cvt_pk_bf16_f32 v16, v0, v1
	v_pk_mul_f32 v[0:1], v[18:19], v[130:131] op_sel_hi:[1,0]
	s_nop 0
	v_cvt_pk_bf16_f32 v17, v0, v1
	v_pk_mul_f32 v[0:1], v[20:21], v[130:131] op_sel_hi:[1,0]
	s_nop 0
	v_cvt_pk_bf16_f32 v18, v0, v1
	v_pk_mul_f32 v[0:1], v[22:23], v[130:131] op_sel_hi:[1,0]
	s_nop 0
	v_cvt_pk_bf16_f32 v19, v0, v1
	v_pk_mul_f32 v[0:1], v[24:25], v[130:131] op_sel_hi:[1,0]
	s_nop 0
	v_cvt_pk_bf16_f32 v20, v0, v1
	v_pk_mul_f32 v[0:1], v[26:27], v[130:131] op_sel_hi:[1,0]
	s_nop 0
	v_cvt_pk_bf16_f32 v21, v0, v1
	v_pk_mul_f32 v[0:1], v[28:29], v[130:131] op_sel_hi:[1,0]
	v_lshl_add_u32 v28, v128, 1, v147
	v_cvt_pk_bf16_f32 v22, v0, v1
	v_pk_mul_f32 v[0:1], v[48:49], v[130:131] op_sel_hi:[1,0]
; __device__ __forceinline__ unsigned cvt_pk_bf16(float lo, float hi) { const f32x2_t v = {lo, hi}; const bf16x2_t b = __builtin_convertvector(v, bf16x2_t); return __builtin_bit_cast(unsigned, b); }
; __device__ __forceinline__ void attn_prompt_unit(unsigned char* lds, const bf16_t* Q, const bf16_t* Kb, const bf16_t* Vb, bf16_t* MIX, const float* sinks, int unit, int tid) {
;     ...
; #pragma unroll
;         for (int db = 0; db < 2; ++db) { f32x16 o = {0.f,0.f,0.f,0.f,0.f,0.f,0.f,0.f,0.f,0.f,0.f,0.f,0.f,0.f,0.f,0.f};
;             const unsigned char* vp = lds + ATT_VT + (32 * db + l32) * VT_PITCH + (q0 + 4 * hi) * 2;
; #pragma unroll
;             for (int kb = 0; kb < 5; ++kb)
; #pragma unroll
;                 for (int sl = 0; sl < 2; ++sl) { const u32x2 lo = *(const u32x2*)(vp + (32 * kb + 16 * sl) * 2), hi2 = *(const u32x2*)(vp + (32 * kb + 16 * sl + 8) * 2);
;                     const bf16x8 vf = __builtin_bit_cast(bf16x8, (u32x4){lo.x, lo.y, hi2.x, hi2.y});
;                     o = __builtin_amdgcn_mfma_f32_32x32x16_bf16(vf, P[kb][sl], o, 0, 0, 0); }
;             bf16_t* op = MIX + qrow * 1024 + head * 64 + 32 * db + 4 * hi;
; #pragma unroll
;             for (int r4 = 0; r4 < 4; ++r4) *(u32x2*)(op + 8 * r4) = (u32x2){cvt_pk_bf16(o[4 * r4], o[4 * r4 + 1]), cvt_pk_bf16(o[4 * r4 + 2], o[4 * r4 + 3])}; }
	v_add_u32_e32 v29, 0x9000, v28
	v_cvt_pk_bf16_f32 v23, v0, v1
	v_pk_mul_f32 v[0:1], v[50:51], v[130:131] op_sel_hi:[1,0]
	s_nop 0
	v_cvt_pk_bf16_f32 v24, v0, v1
	v_pk_mul_f32 v[0:1], v[52:53], v[130:131] op_sel_hi:[1,0]
	s_nop 0
	v_cvt_pk_bf16_f32 v25, v0, v1
	v_pk_mul_f32 v[0:1], v[54:55], v[130:131] op_sel_hi:[1,0]
	s_nop 0
	v_cvt_pk_bf16_f32 v26, v0, v1
	v_pk_mul_f32 v[0:1], v[38:39], v[130:131] op_sel_hi:[1,0]
	s_nop 0
	v_cvt_pk_bf16_f32 v27, v0, v1
	v_pk_mul_f32 v[0:1], v[40:41], v[130:131] op_sel_hi:[1,0]
	s_nop 0
	v_cvt_pk_bf16_f32 v38, v0, v1
	v_pk_mul_f32 v[0:1], v[42:43], v[130:131] op_sel_hi:[1,0]
	s_nop 0
	v_cvt_pk_bf16_f32 v39, v0, v1
	v_pk_mul_f32 v[0:1], v[44:45], v[130:131] op_sel_hi:[1,0]
	s_nop 0
	v_cvt_pk_bf16_f32 v40, v0, v1
	v_pk_mul_f32 v[0:1], v[46:47], v[130:131] op_sel_hi:[1,0]
	s_nop 0
	v_cvt_pk_bf16_f32 v41, v0, v1
	v_pk_mul_f32 v[0:1], v[56:57], v[130:131] op_sel_hi:[1,0]
	s_nop 0
	v_cvt_pk_bf16_f32 v42, v0, v1
	v_pk_mul_f32 v[0:1], v[58:59], v[130:131] op_sel_hi:[1,0]
	s_nop 0
	v_cvt_pk_bf16_f32 v43, v0, v1
	v_pk_mul_f32 v[0:1], v[60:61], v[130:131] op_sel_hi:[1,0]
	s_nop 0
	v_cvt_pk_bf16_f32 v44, v0, v1
	v_pk_mul_f32 v[0:1], v[62:63], v[130:131] op_sel_hi:[1,0]
	s_nop 0
	v_cvt_pk_bf16_f32 v45, v0, v1
	v_pk_mul_f32 v[0:1], v[64:65], v[130:131] op_sel_hi:[1,0]
	v_add_u32_e32 v64, 0xd000, v28
	v_cvt_pk_bf16_f32 v46, v0, v1
	v_pk_mul_f32 v[0:1], v[66:67], v[130:131] op_sel_hi:[1,0]
	s_nop 0
	v_cvt_pk_bf16_f32 v47, v0, v1
	v_pk_mul_f32 v[0:1], v[68:69], v[130:131] op_sel_hi:[1,0]
	s_nop 0
	v_cvt_pk_bf16_f32 v48, v0, v1
	v_pk_mul_f32 v[0:1], v[70:71], v[130:131] op_sel_hi:[1,0]
	s_nop 0
	v_cvt_pk_bf16_f32 v49, v0, v1
	v_pk_mul_f32 v[0:1], v[72:73], v[130:131] op_sel_hi:[1,0]
	s_nop 0
	v_cvt_pk_bf16_f32 v50, v0, v1
	v_pk_mul_f32 v[0:1], v[74:75], v[130:131] op_sel_hi:[1,0]
	s_nop 0
	v_cvt_pk_bf16_f32 v51, v0, v1
	v_pk_mul_f32 v[0:1], v[76:77], v[130:131] op_sel_hi:[1,0]
	s_nop 0
	v_cvt_pk_bf16_f32 v52, v0, v1
	v_pk_mul_f32 v[0:1], v[78:79], v[130:131] op_sel_hi:[1,0]
	s_nop 0
	v_cvt_pk_bf16_f32 v53, v0, v1
	v_pk_mul_f32 v[0:1], v[132:133], v[130:131] op_sel_hi:[1,0]
	s_nop 0
	v_cvt_pk_bf16_f32 v54, v0, v1
	v_pk_mul_f32 v[0:1], v[134:135], v[130:131] op_sel_hi:[1,0]
	s_nop 0
	v_cvt_pk_bf16_f32 v55, v0, v1
	v_pk_mul_f32 v[0:1], v[136:137], v[130:131] op_sel_hi:[1,0]
	s_nop 0
	v_cvt_pk_bf16_f32 v56, v0, v1
	v_pk_mul_f32 v[0:1], v[138:139], v[130:131] op_sel_hi:[1,0]
	s_nop 0
	v_cvt_pk_bf16_f32 v57, v0, v1
	v_lshlrev_b64 v[0:1], 11, v[94:95]
	v_lshl_add_u64 v[62:63], v[92:93], 0, v[0:1]
	ds_read2_b64 v[0:3], v29 offset1:2
	ds_read2_b64 v[58:61], v29 offset0:4 offset1:6
	s_waitcnt lgkmcnt(1)
	v_mfma_f32_32x32x16_bf16 v[0:15], v[0:3], v[30:33], 0
	s_waitcnt lgkmcnt(0)
	v_mfma_f32_32x32x16_bf16 v[0:15], v[58:61], v[34:37], v[0:15]
	ds_read2_b64 v[58:61], v29 offset0:8 offset1:10
	s_waitcnt lgkmcnt(0)
	v_mfma_f32_32x32x16_bf16 v[0:15], v[58:61], v[16:19], v[0:15]
	ds_read2_b64 v[58:61], v29 offset0:12 offset1:14
	s_waitcnt lgkmcnt(0)
	v_mfma_f32_32x32x16_bf16 v[0:15], v[58:61], v[20:23], v[0:15]
	ds_read2_b64 v[58:61], v29 offset0:16 offset1:18
	s_waitcnt lgkmcnt(0)
	v_mfma_f32_32x32x16_bf16 v[0:15], v[58:61], v[24:27], v[0:15]
	ds_read2_b64 v[58:61], v29 offset0:20 offset1:22
	s_waitcnt lgkmcnt(0)
	v_mfma_f32_32x32x16_bf16 v[0:15], v[58:61], v[38:41], v[0:15]
	ds_read2_b64 v[58:61], v29 offset0:24 offset1:26
	s_waitcnt lgkmcnt(0)
	v_mfma_f32_32x32x16_bf16 v[0:15], v[58:61], v[42:45], v[0:15]
	ds_read2_b64 v[58:61], v29 offset0:28 offset1:30
	s_waitcnt lgkmcnt(0)
	v_mfma_f32_32x32x16_bf16 v[0:15], v[58:61], v[46:49], v[0:15]
	ds_read2_b64 v[58:61], v29 offset0:32 offset1:34
	s_waitcnt lgkmcnt(0)
	v_mfma_f32_32x32x16_bf16 v[0:15], v[58:61], v[50:53], v[0:15]
	ds_read2_b64 v[58:61], v29 offset0:36 offset1:38
	s_waitcnt lgkmcnt(0)
	v_mfma_f32_32x32x16_bf16 v[0:15], v[58:61], v[54:57], v[0:15]
	s_nop 11
	v_cvt_pk_bf16_f32 v0, v0, v1
	v_cvt_pk_bf16_f32 v1, v2, v3
	global_store_dwordx2 v[62:63], v[0:1], off
	v_cvt_pk_bf16_f32 v0, v4, v5
	v_cvt_pk_bf16_f32 v1, v6, v7
	global_store_dwordx2 v[62:63], v[0:1], off offset:16
	v_cvt_pk_bf16_f32 v0, v8, v9
	v_cvt_pk_bf16_f32 v1, v10, v11
	global_store_dwordx2 v[62:63], v[0:1], off offset:32
	v_cvt_pk_bf16_f32 v0, v12, v13
	v_cvt_pk_bf16_f32 v1, v14, v15
	global_store_dwordx2 v[62:63], v[0:1], off offset:48
	ds_read2_b64 v[0:3], v64 offset0:64 offset1:66
	ds_read2_b64 v[58:61], v64 offset0:68 offset1:70
	s_waitcnt lgkmcnt(1)
	v_mfma_f32_32x32x16_bf16 v[0:15], v[0:3], v[30:33], 0
	ds_read2_b64 v[28:31], v64 offset0:72 offset1:74
	s_waitcnt lgkmcnt(1)
	v_mfma_f32_32x32x16_bf16 v[0:15], v[58:61], v[34:37], v[0:15]
	s_waitcnt lgkmcnt(0)
	v_mfma_f32_32x32x16_bf16 v[0:15], v[28:31], v[16:19], v[0:15]
	ds_read2_b64 v[16:19], v64 offset0:76 offset1:78
	s_waitcnt lgkmcnt(0)
	v_mfma_f32_32x32x16_bf16 v[0:15], v[16:19], v[20:23], v[0:15]
	ds_read2_b64 v[16:19], v64 offset0:80 offset1:82
	s_waitcnt lgkmcnt(0)
	v_mfma_f32_32x32x16_bf16 v[0:15], v[16:19], v[24:27], v[0:15]
	ds_read2_b64 v[16:19], v64 offset0:84 offset1:86
	s_waitcnt lgkmcnt(0)
	v_mfma_f32_32x32x16_bf16 v[0:15], v[16:19], v[38:41], v[0:15]
	ds_read2_b64 v[16:19], v64 offset0:88 offset1:90
	s_waitcnt lgkmcnt(0)
	v_mfma_f32_32x32x16_bf16 v[0:15], v[16:19], v[42:45], v[0:15]
	ds_read2_b64 v[16:19], v64 offset0:92 offset1:94
	s_waitcnt lgkmcnt(0)
	v_mfma_f32_32x32x16_bf16 v[0:15], v[16:19], v[46:49], v[0:15]
	ds_read2_b64 v[16:19], v64 offset0:96 offset1:98
	s_waitcnt lgkmcnt(0)
	v_mfma_f32_32x32x16_bf16 v[0:15], v[16:19], v[50:53], v[0:15]
	ds_read2_b64 v[16:19], v64 offset0:100 offset1:102
	s_waitcnt lgkmcnt(0)
	v_mfma_f32_32x32x16_bf16 v[0:15], v[16:19], v[54:57], v[0:15]
	s_nop 11
	v_cvt_pk_bf16_f32 v0, v0, v1
	v_cvt_pk_bf16_f32 v1, v2, v3
	global_store_dwordx2 v[62:63], v[0:1], off offset:64
	v_cvt_pk_bf16_f32 v0, v4, v5
	v_cvt_pk_bf16_f32 v1, v6, v7
	global_store_dwordx2 v[62:63], v[0:1], off offset:80
	v_cvt_pk_bf16_f32 v0, v8, v9
	v_cvt_pk_bf16_f32 v1, v10, v11
	global_store_dwordx2 v[62:63], v[0:1], off offset:96
	v_cvt_pk_bf16_f32 v0, v12, v13
	v_cvt_pk_bf16_f32 v1, v14, v15
	global_store_dwordx2 v[62:63], v[0:1], off offset:112
	s_cbranch_vccnz .LBB0_937
	s_add_i32 s15, s15, s39
	s_cmpk_gt_i32 s15, 0xff
	s_cbranch_scc0 .LBB0_928
